# skip dead zero-init VALU on below-diagonal diff tiles; band attention QK: all 8 LDS fragment reads issued up front with counted lgkmcnt
# baseline (speedup 1.0000x reference)
; DI void diff_unit(unsigned char* smem, const bf16* __restrict__ QKV, bf16* __restrict__ Y, int h, int qb, float lam, float outscale, const float* __restrict__ gain, float kn0, float kn1, int tid) {
;     ...
;                 if (j < qb) {
; #pragma unroll
;                     for (int kh = 0; kh < 2; ++kh) { int cio = D3_CI + kh * 64; asm volatile("" : "+v"(cio)); p[kh] = *(const f32x16*)(smem + cio); }
;                 } else {
; #pragma unroll
;                     for (int kh = 0; kh < 2; ++kh)
; #pragma unroll
;                         for (int r = 0; r < 16; ++r) p[kh][r] = 0.f;
;                 }
.Lmy_dma_top_skip:
	v_cmp_lt_i32_e32 vcc, 1, v85
	s_xor_b64 s[16:17], s[38:39], -1
	s_and_b64 s[56:57], vcc, s[16:17]
	s_mov_b64 s[16:17], s[38:39]
	s_and_saveexec_b64 s[54:55], s[56:57]
	s_cbranch_execz .Lmy_dma_stub
	s_add_i32 s81, s45, 0
	v_add_u32_e32 v34, s81, v167
	v_add_u32_e32 v35, s81, v168
	v_add_u32_e32 v36, s81, v169
	v_add_u32_e32 v37, s81, v186
	ds_read_b128 v[140:143], v34
	ds_read_b128 v[144:147], v34 offset:8192
	ds_read_b128 v[136:139], v35
	ds_read_b128 v[132:135], v35 offset:8192
	ds_read_b128 v[128:131], v36
	ds_read_b128 v[42:45], v36 offset:8192
	ds_read_b128 v[38:41], v37
	ds_read_b128 v[34:37], v37 offset:8192
	v_cmp_ge_i32_e32 vcc, v192, v166
	v_cmp_lt_i32_e64 s[16:17], v192, v166
	s_nop 0
	s_cmp_eq_u64 s[16:17], exec
	s_cbranch_scc1 .Lmy_skip_zero_main
	v_mov_b32_e32 v80, 0
	v_mov_b32_e32 v81, v80
	v_mov_b32_e32 v82, v80
	v_mov_b32_e32 v83, v80
	v_mov_b32_e32 v84, v80
	v_mov_b32_e32 v85, v80
	v_mov_b32_e32 v86, v80
	v_mov_b32_e32 v87, v80
	v_mov_b32_e32 v88, v80
	v_mov_b32_e32 v89, v80
	v_mov_b32_e32 v90, v80
	v_mov_b32_e32 v91, v80
	v_mov_b32_e32 v92, v80
	v_mov_b32_e32 v93, v80
	v_mov_b32_e32 v94, v80
	v_mov_b32_e32 v95, v80
	v_mov_b32_e32 v96, v80
	v_mov_b32_e32 v97, v80
	v_mov_b32_e32 v98, v80
	v_mov_b32_e32 v99, v80
	v_mov_b32_e32 v100, v80
	v_mov_b32_e32 v101, v80
	v_mov_b32_e32 v102, v80
	v_mov_b32_e32 v103, v80
	v_mov_b32_e32 v104, v80
	v_mov_b32_e32 v105, v80
	v_mov_b32_e32 v106, v80
	v_mov_b32_e32 v107, v80
	v_mov_b32_e32 v108, v80
	v_mov_b32_e32 v109, v80
	v_mov_b32_e32 v110, v80
	v_mov_b32_e32 v111, v80
.Lmy_skip_zero_main:
	s_and_saveexec_b64 s[56:57], s[16:17]
	s_cbranch_execz .LBB0_212
	v_mov_b32_e32 v80, 0x20080
	v_mov_b32_e32 v96, 0x200c0
	v_add_u32_e32 v92, 0, v80
	s_nop 0
	ds_read_b128 v[80:83], v92
	ds_read_b128 v[84:87], v92 offset:16
	ds_read_b128 v[88:91], v92 offset:32
	ds_read_b128 v[92:95], v92 offset:48
	s_nop 0
	v_add_u32_e32 v108, 0, v96
	ds_read_b128 v[96:99], v108
	ds_read_b128 v[100:103], v108 offset:16
	ds_read_b128 v[104:107], v108 offset:32
	ds_read_b128 v[108:111], v108 offset:48

; #define MFMA32(a, b, c) __builtin_amdgcn_mfma_f32_32x32x16_bf16((a), (b), (c), 0, 0, 0)
; template <int TYPE>
; DI void attn_unit(unsigned char* smem, const bf16* __restrict__ QKV, bf16* __restrict__ Y, int hp, int qb, float lam, float outscale,
;                   const float* __restrict__ gain, const float* __restrict__ relb, int tid, int lane, int wave) {
;     ...
;         if (j <= wj_hi && j >= wj_lo) {
;             f32x16 p[2];
; #pragma unroll
;             for (int kh = 0; kh < 2; ++kh) {
;                 f32x16 acc;
; #pragma unroll
;                 for (int r = 0; r < 16; ++r) acc[r] = 0.f;
; #pragma unroll
;                 for (int ds = 0; ds < 4; ++ds) {
;                     const bf16x8 kf = *(const bf16x8*)(smem + LDS_K + (kh * 32 + r32) * KP + (map * 64 + ds * 16 + 8 * hi) * 2);
;                     acc = MFMA32(kf, qf[ds], acc);
;                 }
;                 p[kh] = acc;
;             }
.LBB0_255:
	s_or_b64 exec, exec, s[10:11]
	v_cmp_le_i32_e32 vcc, v151, v136
	v_cmp_ge_i32_e64 s[10:11], v151, v138
	v_mov_b64_e32 v[16:17], v[50:51]
	v_mov_b64_e32 v[0:1], v[34:35]
	s_and_b64 s[22:23], vcc, s[10:11]
	v_mov_b32_e32 v68, v146
	v_mov_b64_e32 v[18:19], v[52:53]
	v_mov_b64_e32 v[20:21], v[54:55]
	v_mov_b64_e32 v[22:23], v[56:57]
	v_mov_b64_e32 v[24:25], v[58:59]
	v_mov_b64_e32 v[26:27], v[60:61]
	v_mov_b64_e32 v[28:29], v[62:63]
	v_mov_b64_e32 v[30:31], v[64:65]
	v_mov_b64_e32 v[2:3], v[36:37]
	v_mov_b64_e32 v[4:5], v[38:39]
	v_mov_b64_e32 v[6:7], v[40:41]
	v_mov_b64_e32 v[8:9], v[42:43]
	v_mov_b64_e32 v[10:11], v[44:45]
	v_mov_b64_e32 v[12:13], v[46:47]
	v_mov_b64_e32 v[14:15], v[48:49]
	s_and_saveexec_b64 s[10:11], s[22:23]
	s_cbranch_execz .LBB0_261
	ds_read_b128 v[0:3], v144
	ds_read_b128 v[4:7], v144 offset:32
	ds_read_b128 v[186:189], v144 offset:64
	ds_read_b128 v[190:193], v144 offset:96
	ds_read_b128 v[194:197], v144 offset:8704
	ds_read_b128 v[212:215], v144 offset:8736
	ds_read_b128 v[220:223], v144 offset:8768
	ds_read_b128 v[224:227], v144 offset:8800
	v_cmp_ge_i32_e32 vcc, v151, v140
	s_waitcnt lgkmcnt(7)
	v_mfma_f32_32x32x16_bf16 v[66:81], v[0:3], v[106:109], 0
	s_waitcnt lgkmcnt(6)
	v_mfma_f32_32x32x16_bf16 v[66:81], v[4:7], v[98:101], v[66:81]
	s_waitcnt lgkmcnt(5)
	v_mfma_f32_32x32x16_bf16 v[66:81], v[186:189], v[102:105], v[66:81]
	s_waitcnt lgkmcnt(4)
	v_mfma_f32_32x32x16_bf16 v[66:81], v[190:193], v[110:113], v[66:81]
	s_waitcnt lgkmcnt(3)
	v_mfma_f32_32x32x16_bf16 v[82:97], v[194:197], v[106:109], 0
	s_waitcnt lgkmcnt(2)
	v_mfma_f32_32x32x16_bf16 v[82:97], v[212:215], v[98:101], v[82:97]
	s_waitcnt lgkmcnt(1)
	v_mfma_f32_32x32x16_bf16 v[82:97], v[220:223], v[102:105], v[82:97]
	s_waitcnt lgkmcnt(0)
	v_mfma_f32_32x32x16_bf16 v[82:97], v[224:227], v[110:113], v[82:97]
	s_and_saveexec_b64 s[22:23], vcc
	s_xor_b64 s[22:23], exec, s[22:23]
	s_cbranch_execz .LBB0_258
; template <int TYPE>
; DI void attn_unit(unsigned char* smem, const bf16* __restrict__ QKV, bf16* __restrict__ Y, int hp, int qb, float lam, float outscale,
;                   const float* __restrict__ gain, const float* __restrict__ relb, int tid, int lane, int wave) {
;     ...
;                     } else {
;                         const int dq = qpos - kv0;
; #pragma unroll
;                         for (int kh = 0; kh < 2; ++kh)
; #pragma unroll
;                             for (int r = 0; r < 16; ++r) { int rel = dq - (32 * kh + (r & 3) + 8 * (r >> 2)); rel = rel < -63 ? -63 : (rel > 128 ? 128 : rel); p[kh][r] = p[kh][r] * c1 + mytab[rel + 63]; }
;                     }
	v_add_u32_e32 v16, 27, v141
	v_med3_i32 v16, v16, s84, v210
	v_lshl_add_u32 v24, v16, 2, s28
	v_add_u32_e32 v16, 26, v141
	v_med3_i32 v16, v16, s84, v210
	v_lshl_add_u32 v25, v16, 2, s28
	v_add_u32_e32 v16, 25, v141
	v_med3_i32 v16, v16, s84, v210
	v_lshl_add_u32 v26, v16, 2, s28
	v_add_u32_e32 v16, 24, v141
	v_med3_i32 v16, v16, s84, v210
	v_lshl_add_u32 v27, v16, 2, s28
	v_add_u32_e32 v16, 19, v141
	v_med3_i32 v16, v16, s84, v210
	v_lshl_add_u32 v28, v16, 2, s28
	v_add_u32_e32 v16, 18, v141
	v_med3_i32 v16, v16, s84, v210
	v_lshl_add_u32 v29, v16, 2, s28
	v_add_u32_e32 v16, 17, v141
	v_med3_i32 v16, v16, s84, v210
	v_lshl_add_u32 v30, v16, 2, s28
	v_add_u32_e32 v16, 16, v141
	v_med3_i32 v16, v16, s84, v210
	v_add_u32_e32 v0, 59, v141
	v_add_u32_e32 v1, 58, v141
	v_add_u32_e32 v2, 57, v141
	v_add_u32_e32 v3, 56, v141
	v_add_u32_e32 v4, 51, v141
	v_add_u32_e32 v5, 50, v141
	v_add_u32_e32 v6, 49, v141
	v_add_u32_e32 v7, 48, v141
	v_add_u32_e32 v8, 43, v141
	v_add_u32_e32 v9, 42, v141
	v_add_u32_e32 v10, 41, v141
	v_add_u32_e32 v11, 40, v141
	v_add_u32_e32 v12, 35, v141
	v_add_u32_e32 v13, 34, v141
	v_add_u32_e32 v14, 33, v141
	v_add_u32_e32 v15, 32, v141
	v_lshl_add_u32 v31, v16, 2, s28
	v_add_u32_e32 v16, 11, v141
	v_add_u32_e32 v17, 10, v141
	v_add_u32_e32 v18, 9, v141
	v_add_u32_e32 v19, 8, v141
	v_add_u32_e32 v20, 3, v141
	v_add_u32_e32 v21, 2, v141
	v_add_u32_e32 v22, 1, v141
	v_med3_i32 v0, v0, s84, v210
	v_med3_i32 v1, v1, s84, v210
	v_med3_i32 v2, v2, s84, v210
	v_med3_i32 v3, v3, s84, v210
	v_med3_i32 v4, v4, s84, v210
	v_med3_i32 v5, v5, s84, v210
	v_med3_i32 v6, v6, s84, v210
	v_med3_i32 v7, v7, s84, v210
	v_med3_i32 v8, v8, s84, v210
	v_med3_i32 v9, v9, s84, v210
	v_med3_i32 v10, v10, s84, v210
	v_med3_i32 v11, v11, s84, v210
	v_med3_i32 v12, v12, s84, v210
	v_med3_i32 v13, v13, s84, v210
	v_med3_i32 v14, v14, s84, v210
	v_med3_i32 v15, v15, s84, v210
	v_med3_i32 v16, v16, s84, v210
	v_med3_i32 v17, v17, s84, v210
	v_med3_i32 v18, v18, s84, v210
	v_med3_i32 v19, v19, s84, v210
	v_med3_i32 v20, v20, s84, v210
	v_med3_i32 v21, v21, s84, v210
	v_med3_i32 v22, v22, s84, v210
	v_med3_i32 v23, v141, s84, v210
	v_lshl_add_u32 v0, v0, 2, s28
	v_lshl_add_u32 v1, v1, 2, s28
	v_lshl_add_u32 v2, v2, 2, s28
	v_lshl_add_u32 v3, v3, 2, s28
	v_lshl_add_u32 v4, v4, 2, s28
	v_lshl_add_u32 v5, v5, 2, s28
	v_lshl_add_u32 v6, v6, 2, s28
	v_lshl_add_u32 v7, v7, 2, s28
	v_lshl_add_u32 v8, v8, 2, s28
	v_lshl_add_u32 v9, v9, 2, s28
	v_lshl_add_u32 v10, v10, 2, s28
	v_lshl_add_u32 v11, v11, 2, s28
	v_lshl_add_u32 v12, v12, 2, s28
	v_lshl_add_u32 v13, v13, 2, s28
	v_lshl_add_u32 v14, v14, 2, s28
	v_lshl_add_u32 v15, v15, 2, s28
	v_lshl_add_u32 v16, v16, 2, s28
	v_lshl_add_u32 v17, v17, 2, s28
	v_lshl_add_u32 v18, v18, 2, s28
	v_lshl_add_u32 v19, v19, 2, s28
	v_lshl_add_u32 v20, v20, 2, s28
	v_lshl_add_u32 v21, v21, 2, s28
	v_lshl_add_u32 v22, v22, 2, s28
	v_lshl_add_u32 v23, v23, 2, s28
	ds_read_b32 v0, v0 offset:35068
	ds_read_b32 v1, v1 offset:35068
	ds_read_b32 v2, v2 offset:35068
	ds_read_b32 v3, v3 offset:35068
	ds_read_b32 v4, v4 offset:35068
	ds_read_b32 v5, v5 offset:35068
	ds_read_b32 v6, v6 offset:35068
	ds_read_b32 v7, v7 offset:35068
	ds_read_b32 v8, v8 offset:35068
	ds_read_b32 v9, v9 offset:35068
	ds_read_b32 v10, v10 offset:35068
	ds_read_b32 v11, v11 offset:35068
	ds_read_b32 v12, v12 offset:35068
	ds_read_b32 v13, v13 offset:35068
	ds_read_b32 v14, v14 offset:35068
	ds_read_b32 v15, v15 offset:35068
	ds_read_b32 v16, v16 offset:35068
	ds_read_b32 v17, v17 offset:35068
	ds_read_b32 v18, v18 offset:35068
	ds_read_b32 v19, v19 offset:35068
	ds_read_b32 v20, v20 offset:35068
	ds_read_b32 v21, v21 offset:35068
	ds_read_b32 v22, v22 offset:35068
	ds_read_b32 v23, v23 offset:35068
	ds_read_b32 v152, v24 offset:35068
	ds_read_b32 v153, v25 offset:35068
	ds_read_b32 v154, v26 offset:35068
	ds_read_b32 v155, v27 offset:35068
	ds_read_b32 v156, v28 offset:35068
	ds_read_b32 v157, v29 offset:35068
	ds_read_b32 v158, v30 offset:35068
	ds_read_b32 v159, v31 offset:35068
	s_waitcnt lgkmcnt(8)
	v_pk_fma_f32 v[30:31], v[96:97], s[40:41], v[22:23] op_sel_hi:[1,0,1]
	v_pk_fma_f32 v[28:29], v[94:95], s[40:41], v[20:21] op_sel_hi:[1,0,1]
	v_pk_fma_f32 v[26:27], v[92:93], s[40:41], v[18:19] op_sel_hi:[1,0,1]
	v_pk_fma_f32 v[24:25], v[90:91], s[40:41], v[16:17] op_sel_hi:[1,0,1]
	s_waitcnt lgkmcnt(0)
	v_pk_fma_f32 v[22:23], v[88:89], s[40:41], v[158:159] op_sel_hi:[1,0,1]
	v_pk_fma_f32 v[20:21], v[86:87], s[40:41], v[156:157] op_sel_hi:[1,0,1]
	v_pk_fma_f32 v[18:19], v[84:85], s[40:41], v[154:155] op_sel_hi:[1,0,1]
	v_pk_fma_f32 v[16:17], v[82:83], s[40:41], v[152:153] op_sel_hi:[1,0,1]
	v_pk_fma_f32 v[14:15], v[80:81], s[40:41], v[14:15] op_sel_hi:[1,0,1]
	v_pk_fma_f32 v[12:13], v[78:79], s[40:41], v[12:13] op_sel_hi:[1,0,1]
	v_pk_fma_f32 v[10:11], v[76:77], s[40:41], v[10:11] op_sel_hi:[1,0,1]
	v_pk_fma_f32 v[8:9], v[74:75], s[40:41], v[8:9] op_sel_hi:[1,0,1]
	v_pk_fma_f32 v[6:7], v[72:73], s[40:41], v[6:7] op_sel_hi:[1,0,1]
	v_pk_fma_f32 v[4:5], v[70:71], s[40:41], v[4:5] op_sel_hi:[1,0,1]
	v_pk_fma_f32 v[2:3], v[68:69], s[40:41], v[2:3] op_sel_hi:[1,0,1]
	v_pk_fma_f32 v[0:1], v[66:67], s[40:41], v[0:1] op_sel_hi:[1,0,1]
